# defer the last 3072 weight-transpose items (layer-1 weights) from the prologue to the workgroups that sit out the last in-projection round of layer 0 (re-entering the same transpose loop)
# speedup vs baseline: 1.0093x; 1.0093x over previous
_Z10hybrid_fwd7KParams:
	v_writelane_b32 v255, s0, 0
	v_writelane_b32 v255, s1, 1
	s_load_dwordx4 s[24:27], s[0:1], 0xc0
	s_add_u32 s92, s0, 0xc8
	v_and_b32_e32 v200, 0x3ff, v0
	s_addc_u32 s93, s1, 0
	v_cmp_gt_u32_e32 vcc, 16, v200
	s_and_saveexec_b64 s[4:5], vcc
	v_lshl_add_u32 v1, v200, 2, 0
	v_add_u32_e32 v1, 0x20000, v1
	v_mov_b32_e32 v2, 0
	ds_write_b32 v1, v2
	s_or_b64 exec, exec, s[4:5]
	s_cmp_lg_u32 s2, 0
	s_waitcnt lgkmcnt(0)
	s_barrier
	s_cbranch_scc1 .LBB0_12
	s_add_u32 s6, s24, 0x28060000
	v_lshlrev_b32_e32 v2, 2, v200
	s_addc_u32 s7, s25, 0
	v_lshrrev_b32_e32 v1, 9, v200
	v_mov_b32_e32 v3, 0
	v_add_u32_e32 v4, 0x800, v2
	v_xor_b32_e32 v1, 7, v1
	global_store_dword v2, v3, s[6:7]
	global_store_dword v4, v3, s[6:7]
	v_or_b32_e32 v4, 0x1000, v2
	v_add_u32_e32 v2, 0x1800, v2
	global_store_dword v4, v3, s[6:7]
	global_store_dword v2, v3, s[6:7]
	v_add_u32_e32 v2, 0xa00, v200
	v_or_b32_e32 v4, 0x800, v200
	v_cmp_lt_u32_e32 vcc, 4, v1
	v_cmp_lt_u32_e64 s[4:5], 3, v1
	s_and_saveexec_b64 s[8:9], s[4:5]
	s_cbranch_execz .LBB0_5
	v_lshlrev_b32_e32 v4, 2, v4
	global_store_dword v4, v3, s[6:7]

.LBB0_18:
	s_load_dwordx4 s[24:27], s[0:1], 0xc0
	v_and_b32_e32 v8, 63, v1
	s_andn2_b64 vcc, exec, s[4:5]
	s_waitcnt lgkmcnt(0)
	s_lshl_b32 s2, s26, 3
	v_writelane_b32 v251, s2, 6
	s_nop 1
	v_writelane_b32 v251, s3, 7
	s_cbranch_vccnz .LBB0_34
	s_movk_i32 s90, 0x3f00
	s_mov_b32 s91, 0
.Ltrw_enter:
	s_lshl_b32 s4, s14, 14
	s_add_i32 s4, s4, 0
	s_add_u32 s18, s24, 0x8600000
	v_lshlrev_b32_e32 v2, 2, v8
	s_addc_u32 s19, s25, 0
	v_lshrrev_b32_e32 v6, 4, v8
	v_and_b32_e32 v2, 60, v2
	s_add_u32 s20, s24, 0x6e00000
	s_load_dwordx2 s[8:9], s[0:1], 0xa8
	s_load_dwordx2 s[10:11], s[0:1], 0x58
	s_load_dwordx2 s[12:13], s[0:1], 0x10
	v_mul_u32_u24_e32 v4, 0x84, v2
	v_lshlrev_b32_e32 v5, 1, v6
	s_addc_u32 s21, s25, 0
	v_add3_u32 v7, s4, v4, v5
	v_and_b32_e32 v4, 7, v1
	v_lshrrev_b32_e32 v9, 3, v8
	s_add_u32 s22, s24, 0x6a00000
	v_lshl_add_u32 v5, v4, 4, s4
	v_mul_u32_u24_e32 v25, 0x84, v9
	s_addc_u32 s23, s25, 0
	s_lshl_b32 s7, s54, 9
	s_lshl_b32 s4, s14, 6
	v_lshlrev_b32_e32 v4, 3, v4
	s_add_i32 s28, s7, s4
	s_lshl_b32 s4, s54, 4
	s_lshl_b32 s14, s14, 1
	v_add_u32_e32 v25, v5, v25
	s_mov_b32 s5, 0
	v_mov_b32_e32 v3, 0
	v_or_b32_e32 v10, 8, v9
	v_or_b32_e32 v11, 16, v9
	v_or_b32_e32 v12, 24, v9
	v_or_b32_e32 v13, 32, v9
	v_or_b32_e32 v14, 40, v9
	v_or_b32_e32 v15, 48, v9
	v_or_b32_e32 v16, 56, v9
	s_lshl_b32 s29, s26, 9
	s_add_i32 s30, s4, s14
	s_lshl_b32 s31, s26, 4
	v_or_b32_e32 v17, 0xfff96038, v9
	s_add_i32 s33, s6, 0xffffe580
	v_or_b32_e32 v18, 0xfff96030, v9
	v_or_b32_e32 v19, 0xfff96028, v9
	v_or_b32_e32 v20, 0xfff96020, v9
	v_or_b32_e32 v21, 0xfff96018, v9
	v_or_b32_e32 v22, 0xfff96010, v9
	v_or_b32_e32 v23, 0xfff96008, v9
	v_or_b32_e32 v24, 0xfff96000, v9
	s_mov_b32 s34, 0x8000
	s_mov_b32 s35, 0x10000
	s_mov_b32 s36, 0x18000
	s_mov_b32 s37, 0x20000
	s_mov_b32 s38, 0x28000
	s_mov_b32 s39, 0x30000
	s_mov_b32 s40, 0x38000
	s_mov_b32 s41, 0x40000
	s_mov_b32 s42, 0x48000
	s_mov_b32 s43, 0x50000
	s_mov_b32 s44, 0x58000
	s_mov_b32 s45, 0x60000
	s_mov_b32 s46, 0x68000
	s_mov_b32 s47, 0x70000
	s_mov_b32 s48, 0x78000
	s_movk_i32 s49, 0x7fff
	v_add_u32_e32 v26, 0x420, v25
	v_add_u32_e32 v27, 0x428, v25
	v_add_u32_e32 v28, 0x840, v25
	v_add_u32_e32 v29, 0x848, v25
	v_add_u32_e32 v30, 0xc60, v25
	v_add_u32_e32 v31, 0xc68, v25
	v_add_u32_e32 v32, 0x1080, v25
	v_add_u32_e32 v33, 0x1088, v25
	v_add_u32_e32 v34, 0x14a0, v25
	v_add_u32_e32 v35, 0x14a8, v25
	v_add_u32_e32 v36, 0x18c0, v25
	v_add_u32_e32 v37, 0x18c8, v25
	v_add_u32_e32 v38, 0x1ce0, v25
	v_add_u32_e32 v39, 0x1ce8, v25
	s_movk_i32 s50, 0x98
	s_movk_i32 s51, 0x4000
	s_mov_b32 s52, 0xc000
	s_mov_b32 s53, 0x14000
	s_mov_b32 s54, 0x1c000
	s_mov_b32 s55, 0x24000
	s_mov_b32 s56, 0x2c000
	s_mov_b32 s57, 0x34000
	s_mov_b32 s58, 0x3c000
	s_mov_b32 s59, 0xd400
	s_mov_b32 s60, 0x35000
	s_mov_b32 s61, 0x6a000
	s_mov_b32 s62, 0x9f000
	s_mov_b32 s63, 0xd4000
	s_mov_b32 s64, 0x109000
	s_mov_b32 s65, 0x13e000
	s_mov_b32 s66, 0x173000
	s_mov_b32 s67, 0x1a8000
	s_mov_b32 s68, 0x1dd000
	s_mov_b32 s69, 0x212000
	s_mov_b32 s70, 0x247000
	s_mov_b32 s71, 0x27c000
	s_mov_b32 s72, 0x2b1000
	s_mov_b32 s73, 0x2e6000
	s_mov_b32 s74, 0x31b000
	v_lshlrev_b32_e32 v2, 2, v2
	v_lshlrev_b32_e32 v4, 1, v4
	s_mov_b32 s75, s6
	s_branch .LBB0_21
.LBB0_20:
	v_readlane_b32 s2, v251, 6
	s_add_i32 s75, s75, s2
	s_add_i32 s28, s28, s29
	s_add_i32 s30, s30, s31
	s_add_i32 s33, s33, s2
	s_cmp_ge_i32 s75, s90
	v_readlane_b32 s3, v251, 7
	s_cbranch_scc1 .LBB0_33

.LBB0_33:
	v_readlane_b32 s54, v251, 0
	s_cmp_lg_u32 s91, 0
	s_cbranch_scc1 .Ltrw_return

.LBB0_654:
	s_waitcnt vmcnt(0)
	v_readlane_b32 s34, v250, 18
	v_readlane_b32 s35, v250, 19
	s_barrier
	v_readlane_b32 s0, v250, 21
	s_cmp_lg_u32 s0, 0
	s_cbranch_scc1 .Ltrw_skip
	v_readlane_b32 s0, v251, 0
	s_cmp_lt_u32 s0, 160
	s_cbranch_scc1 .Ltrw_skip
	v_writelane_b32 v110, s2, 2
	v_writelane_b32 v110, s3, 3
	v_writelane_b32 v110, s4, 4
	v_writelane_b32 v110, s5, 5
	v_writelane_b32 v110, s6, 6
	v_writelane_b32 v110, s7, 7
	v_writelane_b32 v110, s8, 8
	v_writelane_b32 v110, s9, 9
	v_writelane_b32 v110, s10, 10
	v_writelane_b32 v110, s11, 11
	v_writelane_b32 v110, s12, 12
	v_writelane_b32 v110, s13, 13
	v_writelane_b32 v110, s14, 14
	v_writelane_b32 v110, s15, 15
	v_writelane_b32 v110, s16, 16
	v_writelane_b32 v110, s17, 17
	v_writelane_b32 v110, s18, 18
	v_writelane_b32 v110, s19, 19
	v_writelane_b32 v110, s20, 20
	v_writelane_b32 v110, s21, 21
	v_writelane_b32 v110, s22, 22
	v_writelane_b32 v110, s23, 23
	v_writelane_b32 v110, s24, 24
	v_writelane_b32 v110, s25, 25
	v_writelane_b32 v110, s26, 26
	v_writelane_b32 v110, s27, 27
	v_writelane_b32 v110, s28, 28
	v_writelane_b32 v110, s29, 29
	v_writelane_b32 v110, s30, 30
	v_writelane_b32 v110, s31, 31
	v_writelane_b32 v110, s32, 32
	v_writelane_b32 v110, s33, 33
	v_writelane_b32 v110, s34, 34
	v_writelane_b32 v110, s35, 35
	v_writelane_b32 v110, s36, 36
	v_writelane_b32 v110, s37, 37
	v_writelane_b32 v110, s38, 38
	v_writelane_b32 v110, s39, 39
	v_writelane_b32 v110, s40, 40
	v_writelane_b32 v110, s41, 41
	v_writelane_b32 v110, s42, 42
	v_writelane_b32 v110, s43, 43
	v_writelane_b32 v110, s44, 44
	v_writelane_b32 v110, s45, 45
	v_writelane_b32 v110, s46, 46
	v_writelane_b32 v110, s47, 47
	v_writelane_b32 v110, s48, 48
	v_writelane_b32 v110, s49, 49
	v_writelane_b32 v110, s50, 50
	v_writelane_b32 v110, s51, 51
	v_writelane_b32 v110, s52, 52
	v_writelane_b32 v110, s53, 53
	v_writelane_b32 v110, s54, 54
	v_writelane_b32 v110, s55, 55
	v_writelane_b32 v110, s56, 56
	v_writelane_b32 v110, s57, 57
	v_writelane_b32 v110, s58, 58
	v_writelane_b32 v110, s59, 59
	v_writelane_b32 v110, s60, 60
	v_writelane_b32 v110, s61, 61
	v_writelane_b32 v110, s62, 62
	v_writelane_b32 v110, s63, 63
	v_writelane_b32 v111, s64, 0
	v_writelane_b32 v111, s65, 1
	v_writelane_b32 v111, s66, 2
	v_writelane_b32 v111, s67, 3
	v_writelane_b32 v111, s68, 4
	v_writelane_b32 v111, s69, 5
	v_writelane_b32 v111, s70, 6
	v_writelane_b32 v111, s71, 7
	v_writelane_b32 v111, s72, 8
	v_writelane_b32 v111, s73, 9
	v_writelane_b32 v111, s74, 10
	v_writelane_b32 v111, s75, 11
	v_writelane_b32 v111, s76, 12
	v_writelane_b32 v111, s77, 13
	v_writelane_b32 v111, s78, 14
	v_writelane_b32 v111, s79, 15
	v_writelane_b32 v111, s80, 16
	v_writelane_b32 v111, s81, 17
	v_writelane_b32 v111, s82, 18
	v_writelane_b32 v111, s83, 19
	v_writelane_b32 v111, s84, 20
	v_writelane_b32 v111, s85, 21
	v_writelane_b32 v111, s86, 22
	v_writelane_b32 v111, s87, 23
	v_writelane_b32 v111, s88, 24
	v_writelane_b32 v111, s89, 25
	v_writelane_b32 v111, s90, 26
	v_writelane_b32 v111, s91, 27
	v_writelane_b32 v111, s92, 28
	v_writelane_b32 v111, s93, 29
	v_writelane_b32 v111, s94, 30
	v_writelane_b32 v111, s95, 31
	v_writelane_b32 v111, s96, 32
	v_writelane_b32 v111, s97, 33
	v_writelane_b32 v111, s98, 34
	v_writelane_b32 v111, s99, 35
	v_mov_b32_e32 v1, v200
	v_and_b32_e32 v8, 63, v200
	v_readfirstlane_b32 s33, v200
	s_ashr_i32 s14, s33, 6
	v_readlane_b32 s54, v251, 0
	s_add_i32 s54, s54, 1856
	s_lshl_b32 s2, s54, 3
	s_add_i32 s6, s14, s2
	s_mov_b32 s26, 96
	s_movk_i32 s2, 0x300
	v_writelane_b32 v251, s2, 6
	v_readlane_b32 s24, v251, 1
	v_readlane_b32 s25, v251, 2
	v_readlane_b32 s0, v255, 0
	v_readlane_b32 s1, v255, 1
	s_movk_i32 s90, 0x4b00
	s_mov_b32 s91, 1
	s_branch .Ltrw_enter
.Ltrw_return:
	v_readlane_b32 s2, v110, 26
	s_lshl_b32 s2, s2, 3
	v_writelane_b32 v251, s2, 6
	v_mov_b32_e32 v1, 0
	v_readlane_b32 s2, v110, 2
	v_readlane_b32 s3, v110, 3
	v_readlane_b32 s4, v110, 4
	v_readlane_b32 s5, v110, 5
	v_readlane_b32 s6, v110, 6
	v_readlane_b32 s7, v110, 7
	v_readlane_b32 s8, v110, 8
	v_readlane_b32 s9, v110, 9
	v_readlane_b32 s10, v110, 10
	v_readlane_b32 s11, v110, 11
	v_readlane_b32 s12, v110, 12
	v_readlane_b32 s13, v110, 13
	v_readlane_b32 s14, v110, 14
	v_readlane_b32 s15, v110, 15
	v_readlane_b32 s16, v110, 16
	v_readlane_b32 s17, v110, 17
	v_readlane_b32 s18, v110, 18
	v_readlane_b32 s19, v110, 19
	v_readlane_b32 s20, v110, 20
	v_readlane_b32 s21, v110, 21
	v_readlane_b32 s22, v110, 22
	v_readlane_b32 s23, v110, 23
	v_readlane_b32 s24, v110, 24
	v_readlane_b32 s25, v110, 25
	v_readlane_b32 s26, v110, 26
	v_readlane_b32 s27, v110, 27
	v_readlane_b32 s28, v110, 28
	v_readlane_b32 s29, v110, 29
	v_readlane_b32 s30, v110, 30
	v_readlane_b32 s31, v110, 31
	v_readlane_b32 s32, v110, 32
	v_readlane_b32 s33, v110, 33
	v_readlane_b32 s34, v110, 34
	v_readlane_b32 s35, v110, 35
	v_readlane_b32 s36, v110, 36
	v_readlane_b32 s37, v110, 37
	v_readlane_b32 s38, v110, 38
	v_readlane_b32 s39, v110, 39
	v_readlane_b32 s40, v110, 40
	v_readlane_b32 s41, v110, 41
	v_readlane_b32 s42, v110, 42
	v_readlane_b32 s43, v110, 43
	v_readlane_b32 s44, v110, 44
	v_readlane_b32 s45, v110, 45
	v_readlane_b32 s46, v110, 46
	v_readlane_b32 s47, v110, 47
	v_readlane_b32 s48, v110, 48
	v_readlane_b32 s49, v110, 49
	v_readlane_b32 s50, v110, 50
	v_readlane_b32 s51, v110, 51
	v_readlane_b32 s52, v110, 52
	v_readlane_b32 s53, v110, 53
	v_readlane_b32 s54, v110, 54
	v_readlane_b32 s55, v110, 55
	v_readlane_b32 s56, v110, 56
	v_readlane_b32 s57, v110, 57
	v_readlane_b32 s58, v110, 58
	v_readlane_b32 s59, v110, 59
	v_readlane_b32 s60, v110, 60
	v_readlane_b32 s61, v110, 61
	v_readlane_b32 s62, v110, 62
	v_readlane_b32 s63, v110, 63
	v_readlane_b32 s64, v111, 0
	v_readlane_b32 s65, v111, 1
	v_readlane_b32 s66, v111, 2
	v_readlane_b32 s67, v111, 3
	v_readlane_b32 s68, v111, 4
	v_readlane_b32 s69, v111, 5
	v_readlane_b32 s70, v111, 6
	v_readlane_b32 s71, v111, 7
	v_readlane_b32 s72, v111, 8
	v_readlane_b32 s73, v111, 9
	v_readlane_b32 s74, v111, 10
	v_readlane_b32 s75, v111, 11
	v_readlane_b32 s76, v111, 12
	v_readlane_b32 s77, v111, 13
	v_readlane_b32 s78, v111, 14
	v_readlane_b32 s79, v111, 15
	v_readlane_b32 s80, v111, 16
	v_readlane_b32 s81, v111, 17
	v_readlane_b32 s82, v111, 18
	v_readlane_b32 s83, v111, 19
	v_readlane_b32 s84, v111, 20
	v_readlane_b32 s85, v111, 21
	v_readlane_b32 s86, v111, 22
	v_readlane_b32 s87, v111, 23
	v_readlane_b32 s88, v111, 24
	v_readlane_b32 s89, v111, 25
	v_readlane_b32 s90, v111, 26
	v_readlane_b32 s91, v111, 27
	v_readlane_b32 s92, v111, 28
	v_readlane_b32 s93, v111, 29
	v_readlane_b32 s94, v111, 30
	v_readlane_b32 s95, v111, 31
	v_readlane_b32 s96, v111, 32
	v_readlane_b32 s97, v111, 33
	v_readlane_b32 s98, v111, 34
	v_readlane_b32 s99, v111, 35
	s_nop 4
.Ltrw_skip:
.LBB0_655:
	s_waitcnt vmcnt(0)
	s_waitcnt vmcnt(0) lgkmcnt(0)
	s_barrier
	s_mov_b64 s[0:1], exec
	v_readlane_b32 s2, v251, 8
	v_readlane_b32 s3, v251, 9
	s_and_b64 s[2:3], s[0:1], s[2:3]
	s_mov_b64 exec, s[2:3]
	s_cbranch_execz .LBB0_707
	v_readlane_b32 s2, v254, 26
	s_waitcnt vmcnt(0) expcnt(0) lgkmcnt(0)
	s_nop 0
	v_mov_b32_e32 v0, s2
	ds_read_b32 v3, v0
	v_readlane_b32 s2, v254, 27
	s_waitcnt lgkmcnt(0)
	v_cmp_ne_u32_e32 vcc, 0, v3
	v_mov_b32_e32 v0, s2
	ds_read_b32 v2, v0
	s_cbranch_vccnz .LBB0_671
	s_mov_b32 s10, 1
	s_branch .LBB0_659

	.amdhsa_kernel _Z10hybrid_fwd7KParams
		.amdhsa_group_segment_fixed_size 0
		.amdhsa_private_segment_fixed_size 0
		.amdhsa_kernarg_size 456
		.amdhsa_user_sgpr_count 2
		.amdhsa_user_sgpr_dispatch_ptr 0
		.amdhsa_user_sgpr_queue_ptr 0
		.amdhsa_user_sgpr_kernarg_segment_ptr 1
		.amdhsa_user_sgpr_dispatch_id 0
		.amdhsa_user_sgpr_kernarg_preload_length 0
		.amdhsa_user_sgpr_kernarg_preload_offset 0
		.amdhsa_user_sgpr_private_segment_size 0
		.amdhsa_uses_dynamic_stack 0
		.amdhsa_enable_private_segment 0
		.amdhsa_system_sgpr_workgroup_id_x 1
		.amdhsa_system_sgpr_workgroup_id_y 0
		.amdhsa_system_sgpr_workgroup_id_z 0
		.amdhsa_system_sgpr_workgroup_info 0
		.amdhsa_system_vgpr_workitem_id 2
		.amdhsa_next_free_vgpr 256
		.amdhsa_next_free_sgpr 100
		.amdhsa_accum_offset 256
		.amdhsa_reserve_vcc 1
		.amdhsa_float_round_mode_32 0
		.amdhsa_float_round_mode_16_64 0
		.amdhsa_float_denorm_mode_32 3
		.amdhsa_float_denorm_mode_16_64 3
		.amdhsa_dx10_clamp 1
		.amdhsa_ieee_mode 1
		.amdhsa_fp16_overflow 0
		.amdhsa_tg_split 0
		.amdhsa_exception_fp_ieee_invalid_op 0
		.amdhsa_exception_fp_denorm_src 0
		.amdhsa_exception_fp_ieee_div_zero 0
		.amdhsa_exception_fp_ieee_overflow 0
		.amdhsa_exception_fp_ieee_underflow 0
		.amdhsa_exception_fp_ieee_inexact 0
		.amdhsa_exception_int_div_zero 0
	.end_amdhsa_kernel

.Lfunc_end0:
	.size	_Z10hybrid_fwd7KParams, .Lfunc_end0-_Z10hybrid_fwd7KParams
	.set _Z10hybrid_fwd7KParams.num_vgpr, 256
	.set _Z10hybrid_fwd7KParams.num_agpr, 0
	.set _Z10hybrid_fwd7KParams.numbered_sgpr, 100
	.set _Z10hybrid_fwd7KParams.num_named_barrier, 0
	.set _Z10hybrid_fwd7KParams.private_seg_size, 0
	.set _Z10hybrid_fwd7KParams.uses_vcc, 1
	.set _Z10hybrid_fwd7KParams.uses_flat_scratch, 0
	.set _Z10hybrid_fwd7KParams.has_dyn_sized_stack, 0
	.set _Z10hybrid_fwd7KParams.has_recursion, 0
	.set _Z10hybrid_fwd7KParams.has_indirect_call, 0

amdhsa.kernels:
  - .agpr_count:     0
    .args:
      - .offset:         0
        .size:           200
        .value_kind:     by_value
      - .offset:         200
        .size:           4
        .value_kind:     hidden_block_count_x
      - .offset:         204
        .size:           4
        .value_kind:     hidden_block_count_y
      - .offset:         208
        .size:           4
        .value_kind:     hidden_block_count_z
      - .offset:         212
        .size:           2
        .value_kind:     hidden_group_size_x
      - .offset:         214
        .size:           2
        .value_kind:     hidden_group_size_y
      - .offset:         216
        .size:           2
        .value_kind:     hidden_group_size_z
      - .offset:         218
        .size:           2
        .value_kind:     hidden_remainder_x
      - .offset:         220
        .size:           2
        .value_kind:     hidden_remainder_y
      - .offset:         222
        .size:           2
        .value_kind:     hidden_remainder_z
      - .offset:         240
        .size:           8
        .value_kind:     hidden_global_offset_x
      - .offset:         248
        .size:           8
        .value_kind:     hidden_global_offset_y
      - .offset:         256
        .size:           8
        .value_kind:     hidden_global_offset_z
      - .offset:         264
        .size:           2
        .value_kind:     hidden_grid_dims
      - .offset:         288
        .size:           8
        .value_kind:     hidden_multigrid_sync_arg
      - .offset:         320
        .size:           4
        .value_kind:     hidden_dynamic_lds_size
    .group_segment_fixed_size: 0
    .kernarg_segment_align: 8
    .kernarg_segment_size: 456
    .language:       OpenCL C
    .language_version:
      - 2
      - 0
    .max_flat_workgroup_size: 512
    .name:           _Z10hybrid_fwd7KParams
    .private_segment_fixed_size: 0
    .sgpr_count:     106
    .sgpr_spill_count: 327
    .symbol:         _Z10hybrid_fwd7KParams.kd
    .uniform_work_group_size: 1
    .uses_dynamic_stack: false
    .vgpr_count:     256
    .vgpr_spill_count: 0
    .wavefront_size: 64
